# up K-loop: one static s_setprio 1 for waves 4-7 before the unit loop, the 16 per-phase s_setprio flips of the loop deleted
# baseline (speedup 1.0000x reference)
.LBB0_41:
	v_readlane_b32 s34, v239, 29
	v_readlane_b32 s35, v239, 30
	s_add_u32 s90, s34, 0x10100000
	s_sext_i32_i16 s3, s12
	s_addc_u32 s91, s35, 0
	s_mul_i32 s12, s79, 0x10800
	s_mul_hi_i32 s7, s79, 0x10800
	s_waitcnt lgkmcnt(0)
	s_add_u32 s70, s50, s12
	s_addc_u32 s71, s51, s7
	s_mul_i32 s12, s79, 0x5800
	v_readlane_b32 s52, v239, 21
	s_mul_hi_i32 s7, s79, 0x5800
	v_readlane_b32 s53, v239, 22
	s_add_u32 s34, s52, s12
	s_addc_u32 s35, s53, s7
	s_and_b32 s7, s33, 3
	v_and_b32_e32 v14, 48, v211
	v_lshlrev_b32_e32 v15, 6, v211
	s_movk_i32 s33, 0x3c0
	s_lshl_b32 s12, s15, 6
	v_and_or_b32 v14, v15, s33, v14
	v_lshlrev_b32_e32 v15, 2, v211
	v_readlane_b32 s54, v239, 23
	v_readlane_b32 s55, v239, 24
	v_readlane_b32 s56, v239, 25
	v_readlane_b32 s57, v239, 26
	v_readlane_b32 s58, v239, 27
	v_readlane_b32 s59, v239, 28
	v_writelane_b32 v239, s12, 60
	s_lshl_b32 s12, s15, 13
	v_and_b32_e32 v15, 32, v15
	v_bitop3_b32 v16, v14, s12, v15 bitop3:0xde
	s_lshl_b32 s12, s7, 5
	v_writelane_b32 v239, s12, 62
	s_lshl_b32 s12, s7, 12
	s_add_i32 m0, s10, 0x18000
	v_lshl_add_u64 v[6:7], v[6:7], 0, s[0:1]
	v_writelane_b32 v238, s34, 0
	v_bitop3_b32 v188, s12, v14, v15 bitop3:0xf6
	s_waitcnt vmcnt(2)
	s_barrier
	global_load_lds_dwordx4 v[6:7], off
	v_lshl_add_u64 v[4:5], v[4:5], 0, s[0:1]
	s_add_i32 m0, s10, 0x1a000
	s_add_i32 s12, s10, 0x8000
	s_add_i32 s50, s10, 0xa000
	v_writelane_b32 v238, s35, 1
	global_load_lds_dwordx4 v[4:5], off
	v_lshl_add_u64 v[0:1], v[0:1], 0, s[0:1]
	s_mov_b32 m0, s12
	s_add_u32 s34, s8, 0x40080
	global_load_lds_dwordx4 v[0:1], off
	v_lshl_add_u64 v[0:1], v[2:3], 0, s[0:1]
	s_mov_b32 m0, s50
	s_addc_u32 s35, s9, 0
	global_load_lds_dwordx4 v[0:1], off
	s_add_i32 m0, s10, 0x1c000
	v_lshl_add_u64 v[0:1], s[34:35], 0, v[164:165]
	global_load_lds_dwordx4 v[0:1], off
	v_lshl_add_u64 v[0:1], s[34:35], 0, v[160:161]
	s_add_i32 m0, s10, 0x1e000
	s_cmpk_lt_u32 s14, 0x100
	global_load_lds_dwordx4 v[0:1], off
	s_cselect_b64 s[54:55], -1, 0
	s_lshl_b32 s14, s15, 12
	s_lshl_b32 s7, s7, 10
	v_readlane_b32 s34, v240, 59
	v_lshlrev_b32_e32 v0, 14, v8
	s_or_b32 s33, s7, s14
	s_add_i32 s14, s34, s14
	v_and_b32_e32 v0, 0xffff8000, v0
	s_xor_b32 s33, s33, 0x1000
	s_add_i32 s7, s14, s7
	v_lshl_add_u32 v0, v9, 11, v0
	v_and_b32_e32 v1, 1, v8
	s_lshl_b32 s15, s15, 9
	v_writelane_b32 v238, s7, 5
	s_add_i32 s7, s34, s33
	v_lshl_or_b32 v0, v1, 6, v0
	s_add_i32 s7, s7, s15
	v_lshl_add_u32 v168, v10, 1, v0
	v_lshlrev_b32_e32 v0, 14, v12
	s_add_u32 s80, s70, 0x5800
	v_and_b32_e32 v0, 0xffff8000, v0
	s_waitcnt vmcnt(6)
	s_addc_u32 s81, s71, 0
	v_lshl_add_u32 v0, v11, 11, v0
	v_and_b32_e32 v1, 1, v12
	s_add_u32 s86, s70, 0xb000
	v_lshl_or_b32 v0, v1, 6, v0
	s_mov_b64 s[76:77], s[70:71]
	s_addc_u32 s87, s71, 0
	v_mov_b32_e32 v169, v165
	v_lshl_add_u32 v170, v13, 1, v0
	v_bfe_u32 v228, v170, 11, 6
	v_lshlrev_b32_e32 v229, 2, v228
	v_lshrrev_b32_e32 v228, 4, v228
	v_or_b32_e32 v228, v229, v228
	v_and_b32_e32 v228, 63, v228
	v_and_b32_e32 v170, 0xfffe07ff, v170
	v_lshl_or_b32 v170, v228, 11, v170
	v_bfe_u32 v228, v168, 11, 6
	v_lshlrev_b32_e32 v229, 2, v228
	v_lshrrev_b32_e32 v228, 4, v228
	v_or_b32_e32 v228, v229, v228
	v_and_b32_e32 v228, 63, v228
	v_and_b32_e32 v168, 0xfffe07ff, v168
	v_lshl_or_b32 v168, v228, 11, v168
	v_mov_b32_e32 v171, v165
	s_mov_b32 s51, 0
	v_add_u32_e32 v189, 0, v16
	s_mov_b64 s[34:35], s[8:9]
	s_mov_b64 s[14:15], s[4:5]
	s_mov_b64 s[58:59], s[68:69]
	s_mov_b32 s57, vcc_lo
	s_barrier
	v_writelane_b32 v238, s7, 9
	s_and_b64 vcc, exec, s[88:89]
	s_cbranch_vccz .LPRIO_skip48
	s_setprio 1
.LPRIO_skip48:
	s_branch .LBB0_44
.LBB0_42:
	s_mov_b64 s[4:5], 0

.LBB0_48:
	s_add_i32 s52, s8, 2
	s_add_u32 s9, s4, 0xfffc0080
	s_addc_u32 s53, s5, -1
	s_add_i32 s54, 0, 0x10000
	s_cmp_eq_u32 s33, s8
	s_cselect_b32 vcc_hi, s15, s53
	s_cselect_b32 vcc_lo, s14, s9
	s_cselect_b32 s9, s35, s69
	s_cselect_b32 s8, s34, s68
	s_add_i32 s53, 0, 0x14000
	v_add_u32_e32 v140, s54, v188
	v_add_u32_e32 v156, s53, v188
	ds_read_b128 v[128:131], v140
	ds_read_b128 v[132:135], v140 offset:1024
	ds_read_b128 v[136:139], v140 offset:2048
	ds_read_b128 v[140:143], v140 offset:3072
	ds_read_b128 v[144:147], v156
	ds_read_b128 v[148:151], v156 offset:1024
	ds_read_b128 v[152:155], v156 offset:2048
	ds_read_b128 v[156:159], v156 offset:3072
	s_add_i32 m0, s10, 0xc000
	ds_read_b128 v[172:175], v189
	ds_read_b128 v[176:179], v189 offset:1024
	ds_read_b128 v[180:183], v189 offset:2048
	ds_read_b128 v[184:187], v189 offset:3072
	ds_read_b128 v[212:215], v189 offset:4096
	ds_read_b128 v[216:219], v189 offset:5120
	ds_read_b128 v[220:223], v189 offset:6144
	ds_read_b128 v[224:227], v189 offset:7168
	global_load_lds_dwordx4 v170, s[4:5]
	s_add_i32 m0, s10, 0xe000
	s_nop 0
	global_load_lds_dwordx4 v168, s[4:5]
	s_waitcnt vmcnt(8)
	s_waitcnt lgkmcnt(0)
	s_barrier
	s_waitcnt lgkmcnt(0)
	v_mfma_f32_16x16x32_bf16 v[124:127], v[128:131], v[172:175], v[124:127]
	v_mfma_f32_16x16x32_bf16 v[60:63], v[136:139], v[172:175], v[60:63]
	v_mfma_f32_16x16x32_bf16 v[116:119], v[128:131], v[180:183], v[116:119]
	v_mfma_f32_16x16x32_bf16 v[52:55], v[136:139], v[180:183], v[52:55]
	v_mfma_f32_16x16x32_bf16 v[108:111], v[128:131], v[212:215], v[108:111]
	v_mfma_f32_16x16x32_bf16 v[44:47], v[136:139], v[212:215], v[44:47]
	v_mfma_f32_16x16x32_bf16 v[100:103], v[128:131], v[220:223], v[100:103]
	v_mfma_f32_16x16x32_bf16 v[36:39], v[136:139], v[220:223], v[36:39]
	v_mfma_f32_16x16x32_bf16 v[124:127], v[132:135], v[176:179], v[124:127]
	v_mfma_f32_16x16x32_bf16 v[60:63], v[140:143], v[176:179], v[60:63]
	v_mfma_f32_16x16x32_bf16 v[116:119], v[132:135], v[184:187], v[116:119]
	v_mfma_f32_16x16x32_bf16 v[52:55], v[140:143], v[184:187], v[52:55]
	v_mfma_f32_16x16x32_bf16 v[108:111], v[132:135], v[216:219], v[108:111]
	v_mfma_f32_16x16x32_bf16 v[44:47], v[140:143], v[216:219], v[44:47]
	v_mfma_f32_16x16x32_bf16 v[100:103], v[132:135], v[224:227], v[100:103]
	v_mfma_f32_16x16x32_bf16 v[36:39], v[140:143], v[224:227], v[36:39]
	v_mfma_f32_16x16x32_bf16 v[120:123], v[144:147], v[172:175], v[120:123]
	v_mfma_f32_16x16x32_bf16 v[56:59], v[152:155], v[172:175], v[56:59]
	v_mfma_f32_16x16x32_bf16 v[112:115], v[144:147], v[180:183], v[112:115]
	v_mfma_f32_16x16x32_bf16 v[48:51], v[152:155], v[180:183], v[48:51]
	v_mfma_f32_16x16x32_bf16 v[104:107], v[144:147], v[212:215], v[104:107]
	v_mfma_f32_16x16x32_bf16 v[40:43], v[152:155], v[212:215], v[40:43]
	v_mfma_f32_16x16x32_bf16 v[96:99], v[144:147], v[220:223], v[96:99]
	v_mfma_f32_16x16x32_bf16 v[32:35], v[152:155], v[220:223], v[32:35]
	v_mfma_f32_16x16x32_bf16 v[120:123], v[148:151], v[176:179], v[120:123]
	v_mfma_f32_16x16x32_bf16 v[56:59], v[156:159], v[176:179], v[56:59]
	v_mfma_f32_16x16x32_bf16 v[112:115], v[148:151], v[184:187], v[112:115]
	v_mfma_f32_16x16x32_bf16 v[48:51], v[156:159], v[184:187], v[48:51]
	v_mfma_f32_16x16x32_bf16 v[104:107], v[148:151], v[216:219], v[104:107]
	v_mfma_f32_16x16x32_bf16 v[40:43], v[156:159], v[216:219], v[40:43]
	v_mfma_f32_16x16x32_bf16 v[96:99], v[148:151], v[224:227], v[96:99]
	v_mfma_f32_16x16x32_bf16 v[32:35], v[156:159], v[224:227], v[32:35]
	s_barrier
	s_add_i32 s54, s54, s13
	s_mov_b32 m0, s54
	ds_read_b128 v[172:175], v189 offset:16384
	ds_read_b128 v[176:179], v189 offset:17408
	ds_read_b128 v[180:183], v189 offset:18432
	ds_read_b128 v[184:187], v189 offset:19456
	ds_read_b128 v[212:215], v189 offset:20480
	ds_read_b128 v[216:219], v189 offset:21504
	ds_read_b128 v[220:223], v189 offset:22528
	ds_read_b128 v[224:227], v189 offset:23552
	global_load_lds_dwordx4 v164, s[8:9]
	s_add_i32 m0, s54, 0x2000
	s_add_u32 s54, s8, 0x40000
	s_addc_u32 s55, s9, 0
	s_add_i32 s53, s53, s13
	global_load_lds_dwordx4 v160, s[8:9]
	s_mov_b32 m0, s53
	s_nop 0
	global_load_lds_dwordx4 v164, s[54:55]
	s_add_i32 m0, s53, 0x2000
	s_nop 0
	global_load_lds_dwordx4 v160, s[54:55]
	s_mov_b32 m0, s10
	s_nop 0
	global_load_lds_dwordx4 v166, vcc
	s_mov_b32 m0, s11
	s_nop 0
	global_load_lds_dwordx4 v162, vcc
	s_waitcnt vmcnt(8)
	s_waitcnt lgkmcnt(0)
	s_barrier
	s_waitcnt lgkmcnt(0)
	v_mfma_f32_16x16x32_bf16 v[92:95], v[128:131], v[172:175], v[92:95]
	v_mfma_f32_16x16x32_bf16 v[28:31], v[136:139], v[172:175], v[28:31]
	v_mfma_f32_16x16x32_bf16 v[84:87], v[128:131], v[180:183], v[84:87]
	v_mfma_f32_16x16x32_bf16 v[20:23], v[136:139], v[180:183], v[20:23]
	v_mfma_f32_16x16x32_bf16 v[76:79], v[128:131], v[212:215], v[76:79]
	v_mfma_f32_16x16x32_bf16 v[12:15], v[136:139], v[212:215], v[12:15]
	v_mfma_f32_16x16x32_bf16 v[72:75], v[128:131], v[220:223], v[72:75]
	v_mfma_f32_16x16x32_bf16 v[4:7], v[136:139], v[220:223], v[4:7]
	v_mfma_f32_16x16x32_bf16 v[92:95], v[132:135], v[176:179], v[92:95]
	v_mfma_f32_16x16x32_bf16 v[28:31], v[140:143], v[176:179], v[28:31]
	v_mfma_f32_16x16x32_bf16 v[84:87], v[132:135], v[184:187], v[84:87]
	v_mfma_f32_16x16x32_bf16 v[20:23], v[140:143], v[184:187], v[20:23]
	v_mfma_f32_16x16x32_bf16 v[76:79], v[132:135], v[216:219], v[76:79]
	v_mfma_f32_16x16x32_bf16 v[12:15], v[140:143], v[216:219], v[12:15]
	v_mfma_f32_16x16x32_bf16 v[72:75], v[132:135], v[224:227], v[72:75]
	v_mfma_f32_16x16x32_bf16 v[4:7], v[140:143], v[224:227], v[4:7]
	v_mfma_f32_16x16x32_bf16 v[88:91], v[144:147], v[172:175], v[88:91]
	v_mfma_f32_16x16x32_bf16 v[24:27], v[152:155], v[172:175], v[24:27]
	v_mfma_f32_16x16x32_bf16 v[80:83], v[144:147], v[180:183], v[80:83]
	v_mfma_f32_16x16x32_bf16 v[16:19], v[152:155], v[180:183], v[16:19]
	v_mfma_f32_16x16x32_bf16 v[68:71], v[144:147], v[212:215], v[68:71]
	v_mfma_f32_16x16x32_bf16 v[8:11], v[152:155], v[212:215], v[8:11]
	v_mfma_f32_16x16x32_bf16 v[64:67], v[144:147], v[220:223], v[64:67]
	v_mfma_f32_16x16x32_bf16 v[0:3], v[152:155], v[220:223], v[0:3]
	v_mfma_f32_16x16x32_bf16 v[88:91], v[148:151], v[176:179], v[88:91]
	v_mfma_f32_16x16x32_bf16 v[24:27], v[156:159], v[176:179], v[24:27]
	v_mfma_f32_16x16x32_bf16 v[80:83], v[148:151], v[184:187], v[80:83]
	v_mfma_f32_16x16x32_bf16 v[16:19], v[156:159], v[184:187], v[16:19]
	v_mfma_f32_16x16x32_bf16 v[68:71], v[148:151], v[216:219], v[68:71]
	v_mfma_f32_16x16x32_bf16 v[8:11], v[156:159], v[216:219], v[8:11]
	v_mfma_f32_16x16x32_bf16 v[64:67], v[148:151], v[224:227], v[64:67]
	v_mfma_f32_16x16x32_bf16 v[0:3], v[156:159], v[224:227], v[0:3]
	s_barrier
	s_add_i32 s53, 0, 0x18000
	s_add_i32 s56, 0, 0x1c000
	v_add_u32_e32 v140, s53, v188
	v_add_u32_e32 v156, s56, v188
	ds_read_b128 v[128:131], v140
	ds_read_b128 v[132:135], v140 offset:1024
	ds_read_b128 v[136:139], v140 offset:2048
	ds_read_b128 v[140:143], v140 offset:3072
	ds_read_b128 v[144:147], v156
	ds_read_b128 v[148:151], v156 offset:1024
	ds_read_b128 v[152:155], v156 offset:2048
	ds_read_b128 v[156:159], v156 offset:3072
	s_add_u32 s54, vcc_lo, 0x40000
	s_addc_u32 s55, vcc_hi, 0
	s_mov_b32 m0, s72
	s_nop 0
	ds_read_b128 v[172:175], v189 offset:32768
	ds_read_b128 v[176:179], v189 offset:33792
	ds_read_b128 v[180:183], v189 offset:34816
	ds_read_b128 v[184:187], v189 offset:35840
	ds_read_b128 v[212:215], v189 offset:36864
	ds_read_b128 v[216:219], v189 offset:37888
	ds_read_b128 v[220:223], v189 offset:38912
	ds_read_b128 v[224:227], v189 offset:39936
	global_load_lds_dwordx4 v166, s[54:55]
	s_mov_b32 m0, s73
	s_nop 0
	global_load_lds_dwordx4 v162, s[54:55]
	s_waitcnt vmcnt(8)
	s_waitcnt lgkmcnt(0)
	s_barrier
	s_waitcnt lgkmcnt(0)
	v_mfma_f32_16x16x32_bf16 v[124:127], v[128:131], v[172:175], v[124:127]
	v_mfma_f32_16x16x32_bf16 v[60:63], v[136:139], v[172:175], v[60:63]
	v_mfma_f32_16x16x32_bf16 v[116:119], v[128:131], v[180:183], v[116:119]
	v_mfma_f32_16x16x32_bf16 v[52:55], v[136:139], v[180:183], v[52:55]
	v_mfma_f32_16x16x32_bf16 v[108:111], v[128:131], v[212:215], v[108:111]
	v_mfma_f32_16x16x32_bf16 v[44:47], v[136:139], v[212:215], v[44:47]
	v_mfma_f32_16x16x32_bf16 v[100:103], v[128:131], v[220:223], v[100:103]
	v_mfma_f32_16x16x32_bf16 v[36:39], v[136:139], v[220:223], v[36:39]
	v_mfma_f32_16x16x32_bf16 v[124:127], v[132:135], v[176:179], v[124:127]
	v_mfma_f32_16x16x32_bf16 v[60:63], v[140:143], v[176:179], v[60:63]
	v_mfma_f32_16x16x32_bf16 v[116:119], v[132:135], v[184:187], v[116:119]
	v_mfma_f32_16x16x32_bf16 v[52:55], v[140:143], v[184:187], v[52:55]
	v_mfma_f32_16x16x32_bf16 v[108:111], v[132:135], v[216:219], v[108:111]
	v_mfma_f32_16x16x32_bf16 v[44:47], v[140:143], v[216:219], v[44:47]
	v_mfma_f32_16x16x32_bf16 v[100:103], v[132:135], v[224:227], v[100:103]
	v_mfma_f32_16x16x32_bf16 v[36:39], v[140:143], v[224:227], v[36:39]
	v_mfma_f32_16x16x32_bf16 v[120:123], v[144:147], v[172:175], v[120:123]
	v_mfma_f32_16x16x32_bf16 v[56:59], v[152:155], v[172:175], v[56:59]
	v_mfma_f32_16x16x32_bf16 v[112:115], v[144:147], v[180:183], v[112:115]
	v_mfma_f32_16x16x32_bf16 v[48:51], v[152:155], v[180:183], v[48:51]
	v_mfma_f32_16x16x32_bf16 v[104:107], v[144:147], v[212:215], v[104:107]
	v_mfma_f32_16x16x32_bf16 v[40:43], v[152:155], v[212:215], v[40:43]
	v_mfma_f32_16x16x32_bf16 v[96:99], v[144:147], v[220:223], v[96:99]
	v_mfma_f32_16x16x32_bf16 v[32:35], v[152:155], v[220:223], v[32:35]
	v_mfma_f32_16x16x32_bf16 v[120:123], v[148:151], v[176:179], v[120:123]
	v_mfma_f32_16x16x32_bf16 v[56:59], v[156:159], v[176:179], v[56:59]
	v_mfma_f32_16x16x32_bf16 v[112:115], v[148:151], v[184:187], v[112:115]
	v_mfma_f32_16x16x32_bf16 v[48:51], v[156:159], v[184:187], v[48:51]
	v_mfma_f32_16x16x32_bf16 v[104:107], v[148:151], v[216:219], v[104:107]
	v_mfma_f32_16x16x32_bf16 v[40:43], v[156:159], v[216:219], v[40:43]
	v_mfma_f32_16x16x32_bf16 v[96:99], v[148:151], v[224:227], v[96:99]
	v_mfma_f32_16x16x32_bf16 v[32:35], v[156:159], v[224:227], v[32:35]
	s_barrier
	s_add_i32 s53, s53, s13
	s_add_i32 m0, s53, 0xffffff80
	ds_read_b128 v[172:175], v189 offset:49152
	ds_read_b128 v[176:179], v189 offset:50176
	ds_read_b128 v[180:183], v189 offset:51200
	ds_read_b128 v[184:187], v189 offset:52224
	ds_read_b128 v[212:215], v189 offset:53248
	ds_read_b128 v[216:219], v189 offset:54272
	ds_read_b128 v[220:223], v189 offset:55296
	ds_read_b128 v[224:227], v189 offset:56320
	global_load_lds_dwordx4 v164, s[8:9] offset:128
	s_add_i32 m0, s53, 0x1f80
	s_nop 0
	s_add_i32 s53, s56, s13
	global_load_lds_dwordx4 v160, s[8:9] offset:128
	s_add_u32 s8, s8, 0x40080
	s_addc_u32 s9, s9, 0
	s_mov_b32 m0, s53
	s_nop 0
	global_load_lds_dwordx4 v164, s[8:9]
	s_add_i32 m0, s53, 0x2000
	s_nop 0
	global_load_lds_dwordx4 v160, s[8:9]
	s_add_i32 m0, s12, 0xffffff80
	s_nop 0
	global_load_lds_dwordx4 v166, vcc offset:128
	s_add_i32 m0, s50, 0xffffff80
	s_nop 0
	global_load_lds_dwordx4 v162, vcc offset:128
	s_waitcnt vmcnt(8)
	s_waitcnt lgkmcnt(0)
	s_barrier
	s_waitcnt lgkmcnt(0)
	v_mfma_f32_16x16x32_bf16 v[92:95], v[128:131], v[172:175], v[92:95]
	v_mfma_f32_16x16x32_bf16 v[28:31], v[136:139], v[172:175], v[28:31]
	v_mfma_f32_16x16x32_bf16 v[84:87], v[128:131], v[180:183], v[84:87]
	v_mfma_f32_16x16x32_bf16 v[20:23], v[136:139], v[180:183], v[20:23]
	v_mfma_f32_16x16x32_bf16 v[76:79], v[128:131], v[212:215], v[76:79]
	v_mfma_f32_16x16x32_bf16 v[12:15], v[136:139], v[212:215], v[12:15]
	v_mfma_f32_16x16x32_bf16 v[72:75], v[128:131], v[220:223], v[72:75]
	v_mfma_f32_16x16x32_bf16 v[4:7], v[136:139], v[220:223], v[4:7]
	v_mfma_f32_16x16x32_bf16 v[92:95], v[132:135], v[176:179], v[92:95]
	v_mfma_f32_16x16x32_bf16 v[28:31], v[140:143], v[176:179], v[28:31]
	v_mfma_f32_16x16x32_bf16 v[84:87], v[132:135], v[184:187], v[84:87]
	v_mfma_f32_16x16x32_bf16 v[20:23], v[140:143], v[184:187], v[20:23]
	v_mfma_f32_16x16x32_bf16 v[76:79], v[132:135], v[216:219], v[76:79]
	v_mfma_f32_16x16x32_bf16 v[12:15], v[140:143], v[216:219], v[12:15]
	v_mfma_f32_16x16x32_bf16 v[72:75], v[132:135], v[224:227], v[72:75]
	v_mfma_f32_16x16x32_bf16 v[4:7], v[140:143], v[224:227], v[4:7]
	v_mfma_f32_16x16x32_bf16 v[88:91], v[144:147], v[172:175], v[88:91]
	v_mfma_f32_16x16x32_bf16 v[24:27], v[152:155], v[172:175], v[24:27]
	v_mfma_f32_16x16x32_bf16 v[80:83], v[144:147], v[180:183], v[80:83]
	v_mfma_f32_16x16x32_bf16 v[16:19], v[152:155], v[180:183], v[16:19]
	v_mfma_f32_16x16x32_bf16 v[68:71], v[144:147], v[212:215], v[68:71]
	v_mfma_f32_16x16x32_bf16 v[8:11], v[152:155], v[212:215], v[8:11]
	v_mfma_f32_16x16x32_bf16 v[64:67], v[144:147], v[220:223], v[64:67]
	v_mfma_f32_16x16x32_bf16 v[0:3], v[152:155], v[220:223], v[0:3]
	v_mfma_f32_16x16x32_bf16 v[88:91], v[148:151], v[176:179], v[88:91]
	v_mfma_f32_16x16x32_bf16 v[24:27], v[156:159], v[176:179], v[24:27]
	v_mfma_f32_16x16x32_bf16 v[80:83], v[148:151], v[184:187], v[80:83]
	v_mfma_f32_16x16x32_bf16 v[16:19], v[156:159], v[184:187], v[16:19]
	v_mfma_f32_16x16x32_bf16 v[68:71], v[148:151], v[216:219], v[68:71]
	v_mfma_f32_16x16x32_bf16 v[8:11], v[156:159], v[216:219], v[8:11]
	v_mfma_f32_16x16x32_bf16 v[64:67], v[148:151], v[224:227], v[64:67]
	v_mfma_f32_16x16x32_bf16 v[0:3], v[156:159], v[224:227], v[0:3]
	s_barrier
	s_add_u32 s68, s68, 0x100
	s_addc_u32 s69, s69, 0
	s_add_u32 s4, s4, 0x100
	s_addc_u32 s5, s5, 0
	s_cmp_ge_i32 s52, s7
	s_mov_b32 s8, s52
	s_cbranch_scc0 .LBB0_48
	s_mov_b64 s[54:55], s[84:85]
	s_and_b64 vcc, exec, s[54:55]
	s_cbranch_vccz .LBB0_51

.LBB0_65:
	s_setprio 0
	s_waitcnt vmcnt(0)
	v_readlane_b32 s68, v239, 53
	v_readlane_b32 s69, v239, 54
	v_readlane_b32 s70, v239, 55
	v_readlane_b32 s71, v239, 56
	v_readlane_b32 s68, v239, 15
	v_readlane_b32 s69, v239, 16
	v_readlane_b32 s80, v239, 59
	v_readlane_b32 s15, v238, 6
	v_readlane_b32 s33, v238, 7
	s_mov_b64 s[66:67], 0
	s_barrier
